# ret_kv and SWA: per-unit LDS-visibility barrier moved below the next-unit prefetch issue (loads go out before the barrier wait)
# speedup vs baseline: 1.0107x; 1.0038x over previous
; __device__ __forceinline__ void swa_phase(const bf16* QKV, bf16* MIX, const float* sinks, unsigned char* lds) {
;     ...
;         __syncthreads();
; #pragma unroll
;         for (int it = 0; it < 4; ++it) { const int ci = tid + it * NTHR, kj = ci >> 3, c8 = (ci & 7) * 8; *(u32x4*)(Ks + kj * 72 + c8) = pk_[it]; *(u32x4*)(Vs + kj * 72 + c8) = pv_[it]; }
;         __syncthreads();
;         { const int un = u + (int)gridDim.x; if (un < 1024) SWA_FETCH(un); }
.LBB0_272:
	s_add_i32 s19, s14, s70
	s_cmpk_gt_i32 s19, 0x3ff
	s_cselect_b64 s[4:5], -1, 0
	v_writelane_b32 v236, s4, 17
	s_and_b64 vcc, exec, s[4:5]
	s_barrier
	s_waitcnt vmcnt(1)
	ds_write_b128 v58, v[8:11]
	s_waitcnt vmcnt(0)
	ds_write_b128 v58, v[12:15] offset:36864
	ds_write_b128 v62, v[4:7]
	ds_write_b128 v62, v[16:19] offset:36864
	ds_write_b128 v66, v[20:23]
	ds_write_b128 v66, v[24:27] offset:36864
	ds_write_b128 v70, v[28:31]
	ds_write_b128 v70, v[32:35] offset:36864
	s_waitcnt lgkmcnt(0)
	v_writelane_b32 v236, s5, 18
	s_cbranch_vccnz .LBB0_282
	s_ashr_i32 s4, s19, 9
	s_and_b32 s6, s19, 0x7f
	s_ashr_i32 s5, s4, 31
	s_lshl_b64 s[4:5], s[4:5], 14
	s_lshl_b32 s10, s6, 7
	s_cmp_lg_u32 s6, 0
	s_cselect_b64 s[6:7], -1, 0
	s_or_b32 s4, s4, s10
	s_add_u32 s4, s4, 0xffffff80
	v_readlane_b32 s10, v238, 6
	v_mov_b32_e32 v6, v1
	v_mov_b32_e32 v7, v1
	s_addc_u32 s5, s5, -1
	s_and_b32 s24, s19, 0x180
	v_readlane_b32 s11, v238, 7
	v_mov_b32_e32 v4, v1
	v_mov_b32_e32 v5, v1
	v_mov_b64_e32 v[10:11], v[6:7]
	v_mov_b64_e32 v[14:15], v[6:7]
	v_lshl_add_u64 v[36:37], v[54:55], 0, s[24:25]
	s_or_b64 s[16:17], s[10:11], s[6:7]
	v_mov_b64_e32 v[8:9], v[4:5]
	v_mov_b64_e32 v[12:13], v[4:5]
	s_and_saveexec_b64 s[10:11], s[16:17]
	s_cbranch_execz .LBB0_275
	v_lshl_add_u64 v[2:3], s[4:5], 0, v[52:53]
	s_movk_i32 s15, 0xc00
	v_mad_u64_u32 v[12:13], s[16:17], v2, s15, v[36:37]
	v_mov_b32_e32 v0, v13
	v_mad_u64_u32 v[2:3], s[16:17], v3, s15, v[0:1]
	v_mov_b32_e32 v13, v2
	global_load_dwordx4 v[8:11], v[12:13], off offset:2048
	s_nop 0
	global_load_dwordx4 v[12:15], v[12:13], off offset:2560

; __device__ __forceinline__ void swa_phase(const bf16* QKV, bf16* MIX, const float* sinks, unsigned char* lds) {
;     ...
;         __syncthreads();
;         { const int un = u + (int)gridDim.x; if (un < 1024) SWA_FETCH(un); }
;         for (int g = 0; g < 4; ++g) {
;             const int hq = kvh * 4 + g;
;             bf16x8 qf[2];
; #pragma unroll
;             for (int ks = 0; ks < 2; ++ks) qf[ks] = *(const bf16x8*)(QKV + (rowbase + 16 * wave + r16) * QKVW + hq * 64 + 32 * ks + q4 * 8);
;             f32x4 acc[16];
;             const float sink = sinks[hq];
.LBB0_282:
	s_barrier
	v_writelane_b32 v236, s19, 19
	v_writelane_b32 v236, s24, 20
	s_lshr_b32 s4, s14, 3
	s_and_b32 s4, s4, 48
	v_writelane_b32 v236, s25, 21
	v_writelane_b32 v236, s26, 22
	v_writelane_b32 v236, s27, 23
	v_readlane_b32 s58, v237, 0
	v_readlane_b32 s5, v236, 14
	s_add_u32 s82, s5, s4
	v_readlane_b32 s4, v236, 15
	s_addc_u32 s83, s4, 0
	s_and_b32 s4, s18, 0x7f
	s_lshl_b32 s6, s4, 7
	s_lshl_b32 s4, s14, 2
	s_and_b32 s7, s4, 0x600
	s_ashr_i32 s4, s14, 9
	s_ashr_i32 s5, s4, 31
	s_and_b32 s10, s14, 0x7f
	s_lshl_b64 s[4:5], s[4:5], 14
	s_cmp_eq_u32 s10, 0
	v_readlane_b32 s10, v238, 14
	s_cselect_b64 s[74:75], -1, 0
	v_readlane_b32 s11, v238, 15
	s_or_b64 s[10:11], s[10:11], s[74:75]
	v_writelane_b32 v239, s10, 62
	s_or_b32 s4, s4, s6
	v_lshl_add_u64 v[2:3], s[4:5], 0, v[74:75]
	v_writelane_b32 v239, s11, 63
	v_readlane_b32 s10, v238, 16
	v_readlane_b32 s11, v238, 17
	s_or_b64 s[10:11], s[10:11], s[74:75]
	v_writelane_b32 v238, s10, 0
	v_lshl_add_u64 v[36:37], s[4:5], 0, v[72:73]
	v_lshl_add_u64 v[38:39], s[4:5], 0, v[56:57]
	v_writelane_b32 v238, s11, 1
	v_writelane_b32 v236, s18, 16
	v_readlane_b32 s10, v238, 18
	v_readlane_b32 s11, v238, 19
	s_or_b64 s[10:11], s[10:11], s[74:75]
	v_writelane_b32 v238, s10, 2
	v_lshlrev_b64 v[2:3], 11, v[2:3]
	v_lshlrev_b64 v[36:37], 11, v[36:37]
	v_writelane_b32 v238, s11, 3
	v_mov_b32_e32 v0, s7
	v_readlane_b32 s10, v238, 20
	v_readlane_b32 s11, v238, 21
	s_or_b64 s[10:11], s[10:11], s[74:75]
	v_writelane_b32 v238, s10, 4
	v_or_b32_e32 v2, s7, v2
	v_or_b32_e32 v36, s7, v36
	v_writelane_b32 v238, s11, 5
	v_readlane_b32 s60, v237, 2
	v_readlane_b32 s10, v238, 22
	v_readlane_b32 s11, v238, 23
	s_or_b64 s[10:11], s[10:11], s[74:75]
	v_writelane_b32 v239, s10, 44
	v_readlane_b32 s4, v238, 34
	v_readlane_b32 s5, v238, 35
	v_writelane_b32 v239, s11, 45
	v_readlane_b32 s10, v238, 24
	v_readlane_b32 s11, v238, 25
	s_or_b64 s[10:11], s[10:11], s[74:75]
	v_writelane_b32 v239, s10, 46
	s_or_b64 s[4:5], s[4:5], s[74:75]
	v_readlane_b32 s6, v238, 44
	v_writelane_b32 v239, s11, 47
	v_readlane_b32 s10, v238, 26
	v_readlane_b32 s11, v238, 27
	s_or_b64 s[10:11], s[10:11], s[74:75]
	v_writelane_b32 v239, s10, 50
	v_readlane_b32 s14, v238, 48
	v_readlane_b32 s16, v238, 50
	v_writelane_b32 v239, s11, 51
	v_readlane_b32 s10, v238, 28
	v_readlane_b32 s11, v238, 29
	s_or_b64 s[10:11], s[10:11], s[74:75]
	v_writelane_b32 v239, s10, 48
	v_readlane_b32 s18, v238, 52
	v_readlane_b32 s24, v238, 54
	v_writelane_b32 v239, s11, 49
	v_readlane_b32 s10, v238, 30
	v_readlane_b32 s11, v238, 31
	s_or_b64 s[10:11], s[10:11], s[74:75]
	v_writelane_b32 v239, s10, 54
	v_readlane_b32 s26, v238, 56
	v_readlane_b32 s28, v238, 58
	v_writelane_b32 v239, s11, 55
	v_readlane_b32 s10, v238, 32
	v_readlane_b32 s11, v238, 33
	s_or_b64 s[10:11], s[10:11], s[74:75]
	v_writelane_b32 v239, s10, 60
	v_readlane_b32 s30, v238, 60
	v_readlane_b32 s54, v238, 62
	v_writelane_b32 v239, s11, 61
	v_writelane_b32 v239, s4, 56
	v_readlane_b32 s10, v238, 46
	v_readlane_b32 s62, v237, 4
	v_writelane_b32 v239, s5, 57
	v_readlane_b32 s4, v238, 36
	v_readlane_b32 s5, v238, 37
	s_or_b64 s[4:5], s[4:5], s[74:75]
	v_writelane_b32 v236, s4, 24
	v_readlane_b32 s68, v237, 6
	v_readlane_b32 s70, v237, 8
	v_writelane_b32 v236, s5, 25
	v_readlane_b32 s4, v238, 38
	v_readlane_b32 s5, v238, 39
	s_or_b64 s[4:5], s[4:5], s[74:75]
	v_writelane_b32 v236, s4, 26
	v_readlane_b32 s72, v237, 10
	v_readlane_b32 s84, v237, 12
	v_writelane_b32 v236, s5, 27
	v_readlane_b32 s4, v238, 40
	v_readlane_b32 s5, v238, 41
	s_or_b64 s[94:95], s[4:5], s[74:75]
	v_readlane_b32 s4, v238, 42
	v_readlane_b32 s5, v238, 43
	v_readlane_b32 s7, v238, 45
	v_readlane_b32 s11, v238, 47
	v_readlane_b32 s15, v238, 49
	v_readlane_b32 s17, v238, 51
	v_readlane_b32 s19, v238, 53
	v_readlane_b32 s25, v238, 55
	v_readlane_b32 s27, v238, 57
	v_readlane_b32 s29, v238, 59
	v_readlane_b32 s31, v238, 61
	v_readlane_b32 s55, v238, 63
	v_readlane_b32 s59, v237, 1
	v_readlane_b32 s61, v237, 3
	v_readlane_b32 s63, v237, 5
	v_readlane_b32 s69, v237, 7
	v_readlane_b32 s71, v237, 9
	v_readlane_b32 s73, v237, 11
	v_readlane_b32 s85, v237, 13
	s_movk_i32 s88, 0xc00
	s_or_b64 s[4:5], s[4:5], s[74:75]
	s_or_b64 s[6:7], s[6:7], s[74:75]
	s_or_b64 s[10:11], s[10:11], s[74:75]
	s_or_b64 s[14:15], s[14:15], s[74:75]
	s_or_b64 s[16:17], s[16:17], s[74:75]
	s_or_b64 s[18:19], s[18:19], s[74:75]
	s_or_b64 s[24:25], s[24:25], s[74:75]
	s_or_b64 s[26:27], s[26:27], s[74:75]
	s_or_b64 s[28:29], s[28:29], s[74:75]
	s_or_b64 s[30:31], s[30:31], s[74:75]
	s_or_b64 s[54:55], s[54:55], s[74:75]
	s_or_b64 s[58:59], s[58:59], s[74:75]
	s_or_b64 s[60:61], s[60:61], s[74:75]
	s_or_b64 s[62:63], s[62:63], s[74:75]
	s_or_b64 s[68:69], s[68:69], s[74:75]
	s_or_b64 s[70:71], s[70:71], s[74:75]
	s_or_b64 s[72:73], s[72:73], s[74:75]
	s_or_b64 s[74:75], s[84:85], s[74:75]
	v_lshl_add_u64 v[80:81], v[76:77], 0, v[2:3]
	v_mad_u64_u32 v[2:3], s[84:85], v38, s88, v[0:1]
	v_mov_b32_e32 v0, v3
	v_lshl_add_u64 v[82:83], v[76:77], 0, v[36:37]
	v_mad_u64_u32 v[36:37], s[84:85], v39, s88, v[0:1]
	v_mov_b32_e32 v3, v36
	v_lshl_add_u64 v[84:85], v[78:79], 0, v[2:3]
	s_mov_b64 s[84:85], 0
	v_add_co_u32_e32 v190, vcc, 0x6100000, v84
	s_nop 1
	v_addc_co_u32_e32 v191, vcc, 0, v85, vcc
	global_load_dwordx4 v[180:183], v[190:191], off
	global_load_dwordx4 v[184:187], v[190:191], off offset:64
	global_load_dword v188, v1, s[82:83]
	s_waitcnt vmcnt(0)
	s_branch .Lswa_q_ready

; __device__ __forceinline__ void ret_kv_phase(bf16* Z, float* KV, const f32x2v* rope, unsigned char* lds) {
;     ...
;         const int b = u >> 10, h = (u >> 7) & 7, n = u & 127; const size_t rowbase = (size_t)b * SEQ + n * 128;
;         const float lg = log1pf(-exp2f(-5.f - (float)h));
;         __syncthreads();
;     ...
;         { const int un = u + (int)gridDim.x; if (un < 2048) RK_FETCH(un); }
;         const int dtile = wave >> 1;
; #pragma unroll
;         for (int e2 = 0; e2 < 2; ++e2) { const int etile = (wave & 1) * 2 + e2; f32x4 acc = {0.f, 0.f, 0.f, 0.f};
; #pragma unroll
;             for (int k0 = 0; k0 < 128; k0 += 32) acc = __builtin_amdgcn_mfma_f32_16x16x32_bf16(tr_frag(Ks, 72, k0, 16 * dtile, lane), tr_frag(Vs, 72, k0, 16 * etile, lane), acc, 0, 0, 0);
; #pragma unroll
;             for (int jj = 0; jj < 4; ++jj) KV[((size_t)u * 64 + 16 * dtile + q4 * 4 + jj) * 64 + 16 * etile + r16] = acc[jj]; }
.LBB0_423:
	s_barrier
	ds_read_b64_tr_b16 v[68:69], v64
	ds_read_b64_tr_b16 v[70:71], v64 offset:576
	ds_read_b64_tr_b16 v[72:73], v65 offset:18432
	ds_read_b64_tr_b16 v[74:75], v65 offset:19008
	ds_read_b64_tr_b16 v[76:77], v64 offset:4608
	ds_read_b64_tr_b16 v[78:79], v64 offset:5184
	ds_read_b64_tr_b16 v[80:81], v65 offset:23040
	ds_read_b64_tr_b16 v[82:83], v65 offset:23616
	s_ashr_i32 s15, s14, 31
	s_lshl_b64 s[14:15], s[14:15], 14
	s_andn2_b64 vcc, exec, s[16:17]
	s_waitcnt lgkmcnt(4)
	v_mfma_f32_16x16x32_bf16 v[72:75], v[68:71], v[72:75], 0
	s_waitcnt lgkmcnt(0)
	v_mfma_f32_16x16x32_bf16 v[72:75], v[76:79], v[80:83], v[72:75]
	ds_read_b64_tr_b16 v[80:81], v64 offset:9216
	ds_read_b64_tr_b16 v[82:83], v64 offset:9792
	ds_read_b64_tr_b16 v[84:85], v65 offset:27648
	ds_read_b64_tr_b16 v[86:87], v65 offset:28224
	s_waitcnt lgkmcnt(0)
	v_mfma_f32_16x16x32_bf16 v[72:75], v[80:83], v[84:87], v[72:75]
	ds_read_b64_tr_b16 v[84:85], v64 offset:13824
	ds_read_b64_tr_b16 v[86:87], v64 offset:14400
	ds_read_b64_tr_b16 v[88:89], v65 offset:32256
	ds_read_b64_tr_b16 v[90:91], v65 offset:32832
	s_waitcnt lgkmcnt(0)
	v_mfma_f32_16x16x32_bf16 v[72:75], v[84:87], v[88:91], v[72:75]
	v_lshl_add_u64 v[88:89], s[14:15], 0, v[54:55]
	v_lshl_add_u64 v[90:91], v[50:51], 0, v[88:89]
	s_nop 5
	global_store_dword v[90:91], v72, off
	global_store_dword v[90:91], v73, off offset:256
	global_store_dword v[90:91], v74, off offset:512
	global_store_dword v[90:91], v75, off offset:768
	ds_read_b64_tr_b16 v[72:73], v66 offset:18432
	ds_read_b64_tr_b16 v[74:75], v66 offset:19008
	s_mov_b32 s15, s23
	s_mov_b32 s14, s22
	s_waitcnt lgkmcnt(0)
	v_mfma_f32_16x16x32_bf16 v[68:71], v[68:71], v[72:75], 0
	ds_read_b64_tr_b16 v[72:73], v66 offset:23040
	ds_read_b64_tr_b16 v[74:75], v66 offset:23616
	s_waitcnt lgkmcnt(0)
	v_mfma_f32_16x16x32_bf16 v[68:71], v[76:79], v[72:75], v[68:71]
	ds_read_b64_tr_b16 v[72:73], v66 offset:27648
	ds_read_b64_tr_b16 v[74:75], v66 offset:28224
	s_waitcnt lgkmcnt(0)
	v_mfma_f32_16x16x32_bf16 v[68:71], v[80:83], v[72:75], v[68:71]
	ds_read_b64_tr_b16 v[72:73], v66 offset:32256
	ds_read_b64_tr_b16 v[74:75], v66 offset:32832
	s_waitcnt lgkmcnt(0)
	v_mfma_f32_16x16x32_bf16 v[68:71], v[84:87], v[72:75], v[68:71]
	v_lshl_add_u64 v[72:73], v[52:53], 0, v[88:89]
	s_nop 6
	global_store_dword v[72:73], v68, off
	global_store_dword v[72:73], v69, off offset:256
	global_store_dword v[72:73], v70, off offset:512
	global_store_dword v[72:73], v71, off offset:768
	s_cbranch_vccz .LBB0_429
.LBB0_424:
	s_bfe_u32 s22, s14, 0x30007
	v_cvt_f32_ubyte0_e32 v57, s22
	v_sub_f32_e32 v57, 0xc0a00000, v57
	v_cmp_gt_f32_e32 vcc, s54, v57
	s_ashr_i32 s16, s14, 10
	s_ashr_i32 s17, s16, 31
	v_cndmask_b32_e32 v67, 0, v169, vcc
	v_add_f32_e32 v57, v57, v67
	s_lshl_b64 s[16:17], s[16:17], 14
	s_and_b32 s18, s15, 0x3f80
	v_exp_f32_e32 v57, v57
	s_or_b32 s16, s16, s18
	s_and_b64 s[18:19], vcc, exec
	s_cselect_b32 s18, 0xffffffc0, 0
	v_ldexp_f32 v57, v57, s18
	v_sub_f32_e32 v67, 1.0, v57
	v_add_f32_e32 v68, -1.0, v67
	v_sub_f32_e32 v69, v68, v67
	v_add_f32_e32 v69, 1.0, v69
	v_sub_f32_e64 v68, -v57, v68
	v_add_f32_e32 v70, v68, v69
	v_frexp_mant_f32_e32 v71, v67
	v_cvt_f64_f32_e32 v[68:69], v67
	v_frexp_exp_i32_f64_e32 v68, v[68:69]
	v_cmp_gt_f32_e32 vcc, s55, v71
	s_mov_b32 s41, s89
	s_lshl_b32 s40, s22, 7
	v_subbrev_co_u32_e32 v76, vcc, 0, v68, vcc
	v_sub_u32_e32 v68, 0, v76
	v_ldexp_f32 v67, v67, v68
	v_ldexp_f32 v68, v70, v68
	v_add_f32_e32 v70, -1.0, v67
	v_add_f32_e32 v69, 1.0, v70
	v_sub_f32_e32 v69, v67, v69
	v_add_f32_e32 v71, v68, v69
	v_add_f32_e32 v69, 1.0, v67
	v_add_f32_e32 v72, -1.0, v69
	v_sub_f32_e32 v67, v67, v72
	v_add_f32_e32 v67, v68, v67
	v_add_f32_e32 v77, v69, v67
	v_rcp_f32_e32 v78, v77
	v_sub_f32_e32 v68, v77, v69
	v_add_f32_e32 v69, v70, v71
	v_sub_f32_e32 v67, v67, v68
	v_mul_f32_e32 v80, v69, v78
	v_sub_f32_e32 v68, v69, v70
	v_mul_f32_e32 v70, v77, v80
	v_fma_f32 v72, v80, v77, -v70
	v_fmac_f32_e32 v72, v80, v67
	v_sub_f32_e32 v79, v71, v68
	v_add_f32_e32 v68, v70, v72
	v_sub_f32_e32 v71, v69, v68
	v_pk_add_f32 v[74:75], v[68:69], v[70:71] neg_lo:[0,1] neg_hi:[0,1]
	v_mov_b32_e32 v73, v68
	v_pk_add_f32 v[68:69], v[74:75], v[72:73] neg_lo:[0,1] neg_hi:[0,1]
	v_cmp_nlt_f32_e32 vcc, 1.0, v57
	v_add_f32_e32 v69, v79, v69
	v_add_f32_e32 v68, v68, v69
	v_add_f32_e32 v69, v71, v68
	v_mul_f32_e32 v79, v78, v69
	v_mul_f32_e32 v70, v77, v79
	v_fma_f32 v72, v79, v77, -v70
	v_fmac_f32_e32 v72, v79, v67
	v_sub_f32_e32 v67, v71, v69
	v_add_f32_e32 v67, v68, v67
	v_add_f32_e32 v68, v70, v72
	v_sub_f32_e32 v71, v69, v68
	v_pk_add_f32 v[74:75], v[68:69], v[70:71] neg_lo:[0,1] neg_hi:[0,1]
	v_mov_b32_e32 v73, v68
	v_pk_add_f32 v[68:69], v[74:75], v[72:73] neg_lo:[0,1] neg_hi:[0,1]
	s_waitcnt lgkmcnt(0)
	v_add_f32_e32 v67, v67, v69
	v_add_f32_e32 v67, v68, v67
	v_add_f32_e32 v69, v80, v79
	v_add_f32_e32 v67, v71, v67
	v_sub_f32_e32 v68, v69, v80
	v_mul_f32_e32 v67, v78, v67
	v_sub_f32_e32 v68, v79, v68
	v_add_f32_e32 v67, v68, v67
	v_add_f32_e32 v70, v69, v67
	v_mul_f32_e32 v72, v70, v70
	v_fmamk_f32 v68, v72, 0x3e9b6dac, v166
	v_fmaak_f32 v147, v72, v68, 0x3f2aaada
	v_cvt_f32_i32_e32 v68, v76
	v_sub_f32_e32 v69, v70, v69
	v_sub_f32_e32 v67, v67, v69
	v_mul_f32_e32 v69, v70, v72
	v_pk_mul_f32 v[72:73], v[68:69], v[146:147]
	v_ldexp_f32 v71, v70, 1
	v_fma_f32 v70, v68, s58, -v72
	v_fmac_f32_e32 v70, 0xb102e308, v68
	v_pk_add_f32 v[68:69], v[72:73], v[70:71]
	v_ldexp_f32 v67, v67, 1
	v_sub_f32_e32 v71, v69, v71
	v_sub_f32_e32 v71, v73, v71
	v_add_f32_e32 v75, v67, v71
	v_mov_b32_e32 v74, v72
	v_pk_add_f32 v[72:73], v[68:69], v[72:73] neg_lo:[0,1] neg_hi:[0,1]
	v_pk_add_f32 v[76:77], v[68:69], v[74:75]
	v_mov_b32_e32 v71, v68
	v_mov_b32_e32 v73, v77
	v_pk_add_f32 v[78:79], v[70:71], v[72:73] neg_lo:[0,1] neg_hi:[0,1]
	v_pk_add_f32 v[70:71], v[70:71], v[72:73]
	v_mov_b32_e32 v82, v69
	v_pk_add_f32 v[72:73], v[70:71], v[68:69] op_sel:[1,0] op_sel_hi:[0,1] neg_lo:[0,1] neg_hi:[0,1]
	v_pk_add_f32 v[80:81], v[76:77], v[72:73] op_sel_hi:[1,0] neg_lo:[0,1] neg_hi:[0,1]
	v_mov_b32_e32 v76, v77
	v_mov_b32_e32 v77, v71
	v_mov_b32_e32 v83, v72
	v_pk_add_f32 v[72:73], v[76:77], v[82:83] neg_lo:[0,1] neg_hi:[0,1]
	v_mov_b32_e32 v74, v75
	v_mov_b32_e32 v75, v68
	v_pk_add_f32 v[68:69], v[74:75], v[72:73] neg_lo:[0,1] neg_hi:[0,1]
	v_mov_b32_e32 v80, v78
	v_pk_add_f32 v[72:73], v[80:81], v[68:69]
	v_mov_b32_e32 v79, v71
	v_pk_add_f32 v[74:75], v[72:73], v[72:73] op_sel:[0,1] op_sel_hi:[1,0]
	s_barrier
; __device__ __forceinline__ float bf2f(bf16 v) { return __uint_as_float(((unsigned)v) << 16); }
; __device__ __forceinline__ unsigned pk2(float lo, float hi) { unsigned r; asm("v_cvt_pk_bf16_f32 %0, %1, %2" : "=v"(r) : "v"(lo), "v"(hi)); return r; }
; __device__ __forceinline__ void ret_kv_phase(bf16* Z, float* KV, const f32x2v* rope, unsigned char* lds) {
;     ...
;         for (int it = 0; it < 2; ++it) { const int idx = tid + it * NTHR, p4 = (idx & 7) * 4, i = idx >> 3;
;             bf16* zq = Z + (rowbase + i) * EVEN_IN + h * 64 + p4; bf16* zk = zq + 512;
;             const f32x4 c01 = fc0_[it], c23 = fc1_[it];
;             const float cs_[4] = {c01[0], c01[2], c23[0], c23[2]}, sn_[4] = {c01[1], c01[3], c23[1], c23[3]};
;             const u32x2 ql = fql_[it], qh = fqh_[it], kl = fkl_[it], kh = fkh_[it];
;             const float kd = __expf((float)(127 - i) * lg);
;             float q1[4], q2[4], k1[4], k2[4];
; #pragma unroll
;             for (int x = 0; x < 4; ++x) { const int sh = 16 * (x & 1), wi = x >> 1;
;                 const float a1 = bf2f((bf16)(ql[wi] >> sh)), a2 = bf2f((bf16)(qh[wi] >> sh)), b1 = bf2f((bf16)(kl[wi] >> sh)), b2 = bf2f((bf16)(kh[wi] >> sh));
;                 q1[x] = a1 * cs_[x] - a2 * sn_[x]; q2[x] = a1 * sn_[x] + a2 * cs_[x];
;                 k1[x] = (b1 * cs_[x] - b2 * sn_[x]) * 0.125f; k2[x] = (b1 * sn_[x] + b2 * cs_[x]) * 0.125f; }
;             *(u32x2*)zq = (u32x2){pk2(q1[0], q1[1]), pk2(q1[2], q1[3])}; *(u32x2*)(zq + 32) = (u32x2){pk2(q2[0], q2[1]), pk2(q2[2], q2[3])};
;             *(u32x2*)zk = (u32x2){pk2(k1[0], k1[1]), pk2(k1[2], k1[3])}; *(u32x2*)(zk + 32) = (u32x2){pk2(k2[0], k2[1]), pk2(k2[2], k2[3])};
;             *(u32x2*)(Ks + i * 72 + p4) = (u32x2){pk2(k1[0] * kd, k1[1] * kd), pk2(k1[2] * kd, k1[3] * kd)};
;             *(u32x2*)(Ks + i * 72 + 32 + p4) = (u32x2){pk2(k2[0] * kd, k2[1] * kd), pk2(k2[2] * kd, k2[3] * kd)};
	v_pk_add_f32 v[70:71], v[70:71], v[74:75] op_sel:[1,0] op_sel_hi:[0,1]
	v_mov_b32_e32 v73, v70
	v_pk_add_f32 v[76:77], v[72:73], v[78:79] neg_lo:[0,1] neg_hi:[0,1]
	v_mov_b32_e32 v69, v74
	v_sub_f32_e32 v67, v72, v76
	v_pk_add_f32 v[68:69], v[68:69], v[76:77] neg_lo:[0,1] neg_hi:[0,1]
	v_sub_f32_e32 v67, v78, v67
	v_add_f32_e32 v67, v68, v67
	v_add_f32_e32 v67, v67, v69
	v_add_f32_e32 v67, v70, v67
	v_lshl_add_u64 v[68:69], v[46:47], 0, s[40:41]
	v_lshl_add_u64 v[70:71], s[16:17], 0, v[26:27]
	v_mad_u64_u32 v[72:73], s[18:19], v70, s65, v[68:69]
	v_mad_i32_i24 v73, v71, s65, v73
	s_waitcnt vmcnt(12)
	v_lshlrev_b32_e32 v71, 16, v30
	v_lshlrev_b32_e32 v70, 16, v36
	s_waitcnt vmcnt(8)
	v_pk_mul_f32 v[74:75], v[2:3], v[70:71]
	v_pk_mul_f32 v[70:71], v[2:3], v[70:71] op_sel:[1,0] op_sel_hi:[0,1]
	v_add_f32_e32 v77, v70, v71
	v_lshlrev_b32_e32 v71, 16, v34
	v_lshlrev_b32_e32 v70, 16, v32
	v_sub_f32_e32 v76, v74, v75
	v_pk_mul_f32 v[74:75], v[2:3], v[70:71]
	v_pk_mul_f32 v[70:71], v[2:3], v[70:71] op_sel:[1,0] op_sel_hi:[0,1]
	v_add_f32_e32 v70, v70, v71
	v_sub_f32_e32 v74, v74, v75
	v_mul_f32_e32 v79, 0x3e000000, v70
	v_and_b32_e32 v71, 0xffff0000, v30
	v_and_b32_e32 v70, 0xffff0000, v36
	v_mul_f32_e32 v78, 0x3e000000, v74
	v_pk_mul_f32 v[74:75], v[4:5], v[70:71]
	v_pk_mul_f32 v[70:71], v[4:5], v[70:71] op_sel:[1,0] op_sel_hi:[0,1]
	v_add_f32_e32 v81, v70, v71
	v_and_b32_e32 v71, 0xffff0000, v34
	v_and_b32_e32 v70, 0xffff0000, v32
	v_sub_f32_e32 v80, v74, v75
	v_pk_mul_f32 v[74:75], v[4:5], v[70:71]
	v_pk_mul_f32 v[70:71], v[4:5], v[70:71] op_sel:[1,0] op_sel_hi:[0,1]
	v_add_f32_e32 v70, v70, v71
	v_sub_f32_e32 v74, v74, v75
	v_mul_f32_e32 v83, 0x3e000000, v70
	v_lshlrev_b32_e32 v70, 16, v37
	v_lshlrev_b32_e32 v71, 16, v31
	v_mul_f32_e32 v82, 0x3e000000, v74
	v_pk_mul_f32 v[74:75], v[6:7], v[70:71]
	v_pk_mul_f32 v[70:71], v[6:7], v[70:71] op_sel:[1,0] op_sel_hi:[0,1]
	v_add_f32_e32 v85, v70, v71
	v_lshlrev_b32_e32 v71, 16, v35
	v_lshlrev_b32_e32 v70, 16, v33
	v_sub_f32_e32 v84, v74, v75
	v_pk_mul_f32 v[74:75], v[6:7], v[70:71]
	v_pk_mul_f32 v[70:71], v[6:7], v[70:71] op_sel:[1,0] op_sel_hi:[0,1]
	v_add_f32_e32 v70, v70, v71
	v_cndmask_b32_e32 v67, v170, v67, vcc
	v_cmp_neq_f32_e32 vcc, 1.0, v57
	v_sub_f32_e32 v74, v74, v75
	v_mul_f32_e32 v87, 0x3e000000, v70
	v_and_b32_e32 v71, 0xffff0000, v31
	v_and_b32_e32 v70, 0xffff0000, v37
	v_cndmask_b32_e32 v67, v168, v67, vcc
	v_cmp_gt_f32_e32 vcc, s59, v57
	v_mul_f32_e32 v86, 0x3e000000, v74
	v_pk_mul_f32 v[74:75], v[8:9], v[70:71]
	v_pk_mul_f32 v[70:71], v[8:9], v[70:71] op_sel:[1,0] op_sel_hi:[0,1]
	v_cndmask_b32_e64 v57, v67, -v57, vcc
	v_add_f32_e32 v89, v70, v71
	v_and_b32_e32 v71, 0xffff0000, v35
	v_and_b32_e32 v70, 0xffff0000, v33
	v_mul_f32_e32 v67, v57, v58
	v_sub_f32_e32 v88, v74, v75
	v_pk_mul_f32 v[74:75], v[8:9], v[70:71]
	v_pk_mul_f32 v[70:71], v[8:9], v[70:71] op_sel:[1,0] op_sel_hi:[0,1]
	v_mul_f32_e32 v67, 0x3fb8aa3b, v67
	v_add_f32_e32 v70, v70, v71
	v_sub_f32_e32 v74, v74, v75
	v_mul_f32_e32 v75, 0x3e000000, v70
	v_exp_f32_e32 v67, v67
	v_cvt_pk_bf16_f32 v70, v76, v80
	v_cvt_pk_bf16_f32 v71, v84, v88
	global_store_dwordx2 v[72:73], v[70:71], off
	v_cvt_pk_bf16_f32 v70, v77, v81
	v_cvt_pk_bf16_f32 v71, v85, v89
	v_mul_f32_e32 v74, 0x3e000000, v74
	global_store_dwordx2 v[72:73], v[70:71], off offset:64
	v_cvt_pk_bf16_f32 v70, v78, v82
	v_cvt_pk_bf16_f32 v71, v86, v74
	global_store_dwordx2 v[72:73], v[70:71], off offset:1024
	v_cvt_pk_bf16_f32 v70, v79, v83
	v_cvt_pk_bf16_f32 v71, v87, v75
	global_store_dwordx2 v[72:73], v[70:71], off offset:1088
	v_mul_f32_e32 v70, v78, v67
	v_mul_f32_e32 v71, v82, v67
	v_cvt_pk_bf16_f32 v70, v70, v71
	v_mul_f32_e32 v71, v86, v67
	v_mul_f32_e32 v72, v74, v67
	v_cvt_pk_bf16_f32 v71, v71, v72
	v_mul_f32_e32 v72, v79, v67
	v_mul_f32_e32 v73, v83, v67
	v_cvt_pk_bf16_f32 v72, v72, v73
	v_mul_f32_e32 v73, v87, v67
	v_mul_f32_e32 v67, v75, v67
	v_cvt_pk_bf16_f32 v73, v73, v67
	ds_write2_b64 v59, v[70:71], v[72:73] offset1:8
	s_waitcnt vmcnt(11)
; __device__ __forceinline__ float bf2f(bf16 v) { return __uint_as_float(((unsigned)v) << 16); }
; __device__ __forceinline__ unsigned pk2(float lo, float hi) { unsigned r; asm("v_cvt_pk_bf16_f32 %0, %1, %2" : "=v"(r) : "v"(lo), "v"(hi)); return r; }
; __device__ __forceinline__ void ret_kv_phase(bf16* Z, float* KV, const f32x2v* rope, unsigned char* lds) {
;     ...
;         for (int it = 0; it < 2; ++it) { const int idx = tid + it * NTHR, p4 = (idx & 7) * 4, i = idx >> 3;
;             bf16* zq = Z + (rowbase + i) * EVEN_IN + h * 64 + p4; bf16* zk = zq + 512;
;             const f32x4 c01 = fc0_[it], c23 = fc1_[it];
;             const float cs_[4] = {c01[0], c01[2], c23[0], c23[2]}, sn_[4] = {c01[1], c01[3], c23[1], c23[3]};
;             const u32x2 ql = fql_[it], qh = fqh_[it], kl = fkl_[it], kh = fkh_[it];
;             const float kd = __expf((float)(127 - i) * lg);
;             float q1[4], q2[4], k1[4], k2[4];
; #pragma unroll
;             for (int x = 0; x < 4; ++x) { const int sh = 16 * (x & 1), wi = x >> 1;
;                 const float a1 = bf2f((bf16)(ql[wi] >> sh)), a2 = bf2f((bf16)(qh[wi] >> sh)), b1 = bf2f((bf16)(kl[wi] >> sh)), b2 = bf2f((bf16)(kh[wi] >> sh));
;                 q1[x] = a1 * cs_[x] - a2 * sn_[x]; q2[x] = a1 * sn_[x] + a2 * cs_[x];
;                 k1[x] = (b1 * cs_[x] - b2 * sn_[x]) * 0.125f; k2[x] = (b1 * sn_[x] + b2 * cs_[x]) * 0.125f; }
;             *(u32x2*)zq = (u32x2){pk2(q1[0], q1[1]), pk2(q1[2], q1[3])}; *(u32x2*)(zq + 32) = (u32x2){pk2(q2[0], q2[1]), pk2(q2[2], q2[3])};
;             *(u32x2*)zk = (u32x2){pk2(k1[0], k1[1]), pk2(k1[2], k1[3])}; *(u32x2*)(zk + 32) = (u32x2){pk2(k2[0], k2[1]), pk2(k2[2], k2[3])};
;             *(u32x2*)(Ks + i * 72 + p4) = (u32x2){pk2(k1[0] * kd, k1[1] * kd), pk2(k1[2] * kd, k1[3] * kd)};
;             *(u32x2*)(Ks + i * 72 + 32 + p4) = (u32x2){pk2(k2[0] * kd, k2[1] * kd), pk2(k2[2] * kd, k2[3] * kd)};
;             *(u32x4*)(Vs + (idx >> 3) * 72 + (idx & 7) * 8) = fv_[it]; }
;         __syncthreads();
;         { const int un = u + (int)gridDim.x; if (un < 2048) RK_FETCH(un); }
	ds_write_b128 v60, v[10:13] offset:18432
	v_lshl_add_u64 v[70:71], s[16:17], 0, v[28:29]
	v_mad_u64_u32 v[68:69], s[16:17], v70, s65, v[68:69]
	v_mad_i32_i24 v69, v71, s65, v69
	s_waitcnt vmcnt(9)
	v_lshlrev_b32_e32 v71, 16, v42
	v_lshlrev_b32_e32 v70, 16, v44
	s_waitcnt vmcnt(5)
	v_pk_mul_f32 v[72:73], v[14:15], v[70:71]
	v_pk_mul_f32 v[70:71], v[14:15], v[70:71] op_sel:[1,0] op_sel_hi:[0,1]
	v_add_f32_e32 v74, v70, v71
	v_lshlrev_b32_e32 v71, 16, v40
	v_lshlrev_b32_e32 v70, 16, v38
	v_sub_f32_e32 v67, v72, v73
	v_pk_mul_f32 v[72:73], v[14:15], v[70:71]
	v_pk_mul_f32 v[70:71], v[14:15], v[70:71] op_sel:[1,0] op_sel_hi:[0,1]
	v_add_f32_e32 v70, v70, v71
	v_sub_f32_e32 v72, v72, v73
	v_mul_f32_e32 v76, 0x3e000000, v70
	v_and_b32_e32 v71, 0xffff0000, v42
	v_and_b32_e32 v70, 0xffff0000, v44
	v_mul_f32_e32 v75, 0x3e000000, v72
	v_pk_mul_f32 v[72:73], v[16:17], v[70:71]
	v_pk_mul_f32 v[70:71], v[16:17], v[70:71] op_sel:[1,0] op_sel_hi:[0,1]
	v_add_f32_e32 v78, v70, v71
	v_and_b32_e32 v71, 0xffff0000, v40
	v_and_b32_e32 v70, 0xffff0000, v38
	v_sub_f32_e32 v77, v72, v73
	v_pk_mul_f32 v[72:73], v[16:17], v[70:71]
	v_pk_mul_f32 v[70:71], v[16:17], v[70:71] op_sel:[1,0] op_sel_hi:[0,1]
	v_add_f32_e32 v70, v70, v71
	v_sub_f32_e32 v72, v72, v73
	v_mul_f32_e32 v80, 0x3e000000, v70
	v_lshlrev_b32_e32 v70, 16, v45
	v_lshlrev_b32_e32 v71, 16, v43
	v_mul_f32_e32 v79, 0x3e000000, v72
	v_pk_mul_f32 v[72:73], v[18:19], v[70:71]
	v_pk_mul_f32 v[70:71], v[18:19], v[70:71] op_sel:[1,0] op_sel_hi:[0,1]
	v_add_f32_e32 v82, v70, v71
	v_lshlrev_b32_e32 v71, 16, v41
	v_lshlrev_b32_e32 v70, 16, v39
	v_sub_f32_e32 v81, v72, v73
	v_pk_mul_f32 v[72:73], v[18:19], v[70:71]
	v_pk_mul_f32 v[70:71], v[18:19], v[70:71] op_sel:[1,0] op_sel_hi:[0,1]
	v_add_f32_e32 v70, v70, v71
	v_sub_f32_e32 v72, v72, v73
	v_mul_f32_e32 v84, 0x3e000000, v70
	v_and_b32_e32 v71, 0xffff0000, v43
	v_and_b32_e32 v70, 0xffff0000, v45
	v_mul_f32_e32 v83, 0x3e000000, v72
	v_pk_mul_f32 v[72:73], v[20:21], v[70:71]
	v_pk_mul_f32 v[70:71], v[20:21], v[70:71] op_sel:[1,0] op_sel_hi:[0,1]
	v_mul_f32_e32 v57, v57, v61
	v_add_f32_e32 v86, v70, v71
	v_and_b32_e32 v71, 0xffff0000, v41
	v_and_b32_e32 v70, 0xffff0000, v39
	v_mul_f32_e32 v57, 0x3fb8aa3b, v57
	v_sub_f32_e32 v85, v72, v73
	v_pk_mul_f32 v[72:73], v[20:21], v[70:71]
	v_pk_mul_f32 v[70:71], v[20:21], v[70:71] op_sel:[1,0] op_sel_hi:[0,1]
	v_add_f32_e32 v70, v70, v71
	v_exp_f32_e32 v57, v57
	v_sub_f32_e32 v72, v72, v73
	v_mul_f32_e32 v73, 0x3e000000, v70
	v_cvt_pk_bf16_f32 v70, v67, v77
	v_cvt_pk_bf16_f32 v71, v81, v85
	global_store_dwordx2 v[68:69], v[70:71], off
	v_cvt_pk_bf16_f32 v70, v74, v78
	v_cvt_pk_bf16_f32 v71, v82, v86
	v_mul_f32_e32 v72, 0x3e000000, v72
	global_store_dwordx2 v[68:69], v[70:71], off offset:64
	v_cvt_pk_bf16_f32 v70, v75, v79
	v_cvt_pk_bf16_f32 v71, v83, v72
	global_store_dwordx2 v[68:69], v[70:71], off offset:1024
	v_cvt_pk_bf16_f32 v70, v76, v80
	v_cvt_pk_bf16_f32 v71, v84, v73
	global_store_dwordx2 v[68:69], v[70:71], off offset:1088
	v_mul_f32_e32 v67, v75, v57
	v_mul_f32_e32 v68, v79, v57
	v_cvt_pk_bf16_f32 v68, v67, v68
	v_mul_f32_e32 v67, v83, v57
	v_mul_f32_e32 v69, v72, v57
	s_add_i32 s22, s14, s70
	v_cvt_pk_bf16_f32 v69, v67, v69
	v_mul_f32_e32 v67, v76, v57
	v_mul_f32_e32 v70, v80, v57
	s_cmpk_gt_i32 s22, 0x7ff
	v_cvt_pk_bf16_f32 v70, v67, v70
	v_mul_f32_e32 v67, v84, v57
	v_mul_f32_e32 v57, v73, v57
	v_cvt_pk_bf16_f32 v71, v67, v57
	s_cselect_b64 s[16:17], -1, 0
	s_cmpk_lt_i32 s22, 0x800
	s_mov_b64 s[18:19], -1
	ds_write2_b64 v62, v[68:69], v[70:71] offset1:8
	s_waitcnt vmcnt(8)
	ds_write_b128 v63, v[22:25] offset:18432
	s_waitcnt lgkmcnt(0)
	s_cbranch_scc1 .LBB0_426
	v_readlane_b32 s18, v240, 40
	s_add_i32 s23, s15, s18
	s_mov_b64 s[18:19], 0
